# xattn QK^T: 16 MFMAs per key tile unrolled with a 4-deep (K,Q) fragment ring read 3 ahead, counted lgkmcnt waits, C=0 first MFMA
# baseline (speedup 1.0000x reference)
.LBB0_837:
	s_lshl_b32 s0, s17, 6
	s_lshl_b64 s[18:19], s[0:1], 11
	s_lshl_b32 s0, s17, 7
	v_lshl_add_u64 v[130:131], v[164:165], 0, s[0:1]
	v_add_co_u32_e32 v132, vcc, 0x10000, v130
	v_lshl_add_u64 v[128:129], v[162:163], 0, s[18:19]
	s_nop 0
	v_addc_co_u32_e32 v133, vcc, 0, v131, vcc
	global_load_dwordx4 v[214:217], v[128:129], off
	global_load_dwordx4 v[218:221], v[128:129], off offset:128
	global_load_dwordx4 v[222:225], v[130:131], off
	global_load_dwordx4 v[226:229], v[132:133], off
	v_add_co_u32_e32 v132, vcc, s10, v130
	global_load_dwordx4 v[230:233], v[128:129], off offset:256
	global_load_dwordx4 v[234:237], v[128:129], off offset:384
	v_addc_co_u32_e32 v133, vcc, 0, v131, vcc
	v_add_co_u32_e32 v128, vcc, 0x30000, v130
	v_add_u32_e32 v143, v167, v174
	s_nop 0
	v_addc_co_u32_e32 v129, vcc, 0, v131, vcc
	global_load_dwordx4 v[238:241], v[132:133], off
	global_load_dwordx4 v[242:245], v[128:129], off
	s_nop 0
	s_mov_b32 s0, 0
	v_add_u32_e32 v246, v167, v175
	v_add_u32_e32 v247, v167, v176
	v_add_u32_e32 v248, v167, v177
	s_nop 0
	s_waitcnt vmcnt(7)
	ds_write_b128 v143, v[214:217]
	s_waitcnt vmcnt(6)
	ds_write_b128 v246, v[218:221]
	s_waitcnt vmcnt(3)
	ds_write_b128 v247, v[230:233]
	s_waitcnt vmcnt(2)
	ds_write_b128 v248, v[234:237]
	ds_write_b128 v179, v[222:225] offset:32768
	ds_write_b128 v179, v[226:229] offset:40960
	s_waitcnt vmcnt(1)
	ds_write_b128 v179, v[238:241] offset:49152
	s_waitcnt vmcnt(0)
	ds_write_b128 v179, v[242:245] offset:57344
	s_waitcnt lgkmcnt(0)
	s_barrier
.LBB0_838:
	v_xor_b32_e32 v249, v145, v169
	v_lshl_add_u32 v249, v249, 4, v168
	v_xor_b32_e32 v250, v145, v170
	v_lshl_add_u32 v250, v250, 4, v166
	ds_read_b128 v[214:217], v249
	ds_read_b128 v[218:221], v250
	v_xor_b32_e32 v251, 32, v249
	ds_read_b128 v[222:225], v251
	v_xor_b32_e32 v252, 32, v250
	ds_read_b128 v[226:229], v252
	v_xor_b32_e32 v251, 64, v249
	ds_read_b128 v[230:233], v251
	v_xor_b32_e32 v252, 64, v250
	ds_read_b128 v[234:237], v252
	v_xor_b32_e32 v251, 0x60, v249
	ds_read_b128 v[238:241], v251
	v_xor_b32_e32 v252, 0x60, v250
	ds_read_b128 v[242:245], v252
	s_waitcnt lgkmcnt(6)
	v_mfma_f32_32x32x16_bf16 v[128:143], v[214:217], v[218:221], 0
	v_xor_b32_e32 v251, 0x80, v249
	ds_read_b128 v[214:217], v251
	v_xor_b32_e32 v252, 0x80, v250
	ds_read_b128 v[218:221], v252
	s_waitcnt lgkmcnt(6)
	v_mfma_f32_32x32x16_bf16 v[128:143], v[222:225], v[226:229], v[128:143]
	v_xor_b32_e32 v251, 0xa0, v249
	ds_read_b128 v[222:225], v251
	v_xor_b32_e32 v252, 0xa0, v250
	ds_read_b128 v[226:229], v252
	s_waitcnt lgkmcnt(6)
	v_mfma_f32_32x32x16_bf16 v[128:143], v[230:233], v[234:237], v[128:143]
	v_xor_b32_e32 v251, 0xc0, v249
	ds_read_b128 v[230:233], v251
	v_xor_b32_e32 v252, 0xc0, v250
	ds_read_b128 v[234:237], v252
	s_waitcnt lgkmcnt(6)
	v_mfma_f32_32x32x16_bf16 v[128:143], v[238:241], v[242:245], v[128:143]
	v_xor_b32_e32 v251, 0xe0, v249
	ds_read_b128 v[238:241], v251
	v_xor_b32_e32 v252, 0xe0, v250
	ds_read_b128 v[242:245], v252
	s_waitcnt lgkmcnt(6)
	v_mfma_f32_32x32x16_bf16 v[128:143], v[214:217], v[218:221], v[128:143]
	v_xor_b32_e32 v251, 0x100, v249
	ds_read_b128 v[214:217], v251
	v_xor_b32_e32 v252, 0x100, v250
	ds_read_b128 v[218:221], v252
	s_waitcnt lgkmcnt(6)
	v_mfma_f32_32x32x16_bf16 v[128:143], v[222:225], v[226:229], v[128:143]
	v_xor_b32_e32 v251, 0x120, v249
	ds_read_b128 v[222:225], v251
	v_xor_b32_e32 v252, 0x120, v250
	ds_read_b128 v[226:229], v252
	s_waitcnt lgkmcnt(6)
	v_mfma_f32_32x32x16_bf16 v[128:143], v[230:233], v[234:237], v[128:143]
	v_xor_b32_e32 v251, 0x140, v249
	ds_read_b128 v[230:233], v251
	v_xor_b32_e32 v252, 0x140, v250
	ds_read_b128 v[234:237], v252
	s_waitcnt lgkmcnt(6)
	v_mfma_f32_32x32x16_bf16 v[128:143], v[238:241], v[242:245], v[128:143]
	v_xor_b32_e32 v251, 0x160, v249
	ds_read_b128 v[238:241], v251
	v_xor_b32_e32 v252, 0x160, v250
	ds_read_b128 v[242:245], v252
	s_waitcnt lgkmcnt(6)
	v_mfma_f32_32x32x16_bf16 v[128:143], v[214:217], v[218:221], v[128:143]
	v_xor_b32_e32 v251, 0x180, v249
	ds_read_b128 v[214:217], v251
	v_xor_b32_e32 v252, 0x180, v250
	ds_read_b128 v[218:221], v252
	s_waitcnt lgkmcnt(6)
	v_mfma_f32_32x32x16_bf16 v[128:143], v[222:225], v[226:229], v[128:143]
	v_xor_b32_e32 v251, 0x1a0, v249
	ds_read_b128 v[222:225], v251
	v_xor_b32_e32 v252, 0x1a0, v250
	ds_read_b128 v[226:229], v252
	s_waitcnt lgkmcnt(6)
	v_mfma_f32_32x32x16_bf16 v[128:143], v[230:233], v[234:237], v[128:143]
	v_xor_b32_e32 v251, 0x1c0, v249
	ds_read_b128 v[230:233], v251
	v_xor_b32_e32 v252, 0x1c0, v250
	ds_read_b128 v[234:237], v252
	s_waitcnt lgkmcnt(6)
	v_mfma_f32_32x32x16_bf16 v[128:143], v[238:241], v[242:245], v[128:143]
	v_xor_b32_e32 v251, 0x1e0, v249
	ds_read_b128 v[238:241], v251
	v_xor_b32_e32 v252, 0x1e0, v250
	ds_read_b128 v[242:245], v252
	s_waitcnt lgkmcnt(6)
	v_mfma_f32_32x32x16_bf16 v[128:143], v[214:217], v[218:221], v[128:143]
	s_waitcnt lgkmcnt(4)
	v_mfma_f32_32x32x16_bf16 v[128:143], v[222:225], v[226:229], v[128:143]
	s_waitcnt lgkmcnt(2)
	v_mfma_f32_32x32x16_bf16 v[128:143], v[230:233], v[234:237], v[128:143]
	s_waitcnt lgkmcnt(0)
	v_mfma_f32_32x32x16_bf16 v[128:143], v[238:241], v[242:245], v[128:143]
	s_nop 11
	v_subrev_f32_e32 v128, s7, v128
	v_exp_f32_e32 v218, v128
	v_subrev_f32_e32 v128, s7, v129
	v_exp_f32_e32 v219, v128
	v_subrev_f32_e32 v128, s7, v130
	v_exp_f32_e32 v220, v128
	v_subrev_f32_e32 v128, s7, v131
	v_exp_f32_e32 v221, v128
	v_subrev_f32_e32 v128, s7, v132
	v_exp_f32_e32 v222, v128
	v_subrev_f32_e32 v128, s7, v133
	v_exp_f32_e32 v223, v128
	v_subrev_f32_e32 v128, s7, v134
	v_exp_f32_e32 v224, v128
	v_subrev_f32_e32 v128, s7, v135
	v_exp_f32_e32 v225, v128
	v_subrev_f32_e32 v128, s7, v136
	v_exp_f32_e32 v226, v128
	v_subrev_f32_e32 v128, s7, v137
	v_exp_f32_e32 v227, v128
	v_subrev_f32_e32 v128, s7, v138
	v_exp_f32_e32 v228, v128
	v_subrev_f32_e32 v128, s7, v139
	v_exp_f32_e32 v229, v128
	v_subrev_f32_e32 v128, s7, v140
	v_exp_f32_e32 v230, v128
	v_subrev_f32_e32 v128, s7, v141
	v_exp_f32_e32 v231, v128
	ds_read_b128 v[128:131], v180 offset:32768
	ds_read_b128 v[136:139], v181 offset:32768
	ds_read_b128 v[214:217], v180 offset:36864
	v_subrev_f32_e32 v132, s7, v142
	v_exp_f32_e32 v232, v132
	v_cvt_pk_bf16_f32 v132, v218, v219
	v_cvt_pk_bf16_f32 v133, v220, v221
	v_cvt_pk_bf16_f32 v134, v222, v223
	v_cvt_pk_bf16_f32 v135, v224, v225
	v_add_f32_e32 v213, v213, v218
	v_add_f32_e32 v213, v219, v213
	s_waitcnt lgkmcnt(2)
	v_mfma_f32_32x32x16_bf16 v[112:127], v[128:131], v[132:135], v[112:127]
	v_subrev_f32_e32 v128, s7, v143
	ds_read_b128 v[140:143], v181 offset:36864
	v_exp_f32_e32 v233, v128
	v_cvt_pk_bf16_f32 v128, v226, v227
	v_cvt_pk_bf16_f32 v129, v228, v229
	v_cvt_pk_bf16_f32 v130, v230, v231
	v_cvt_pk_bf16_f32 v131, v232, v233
	s_waitcnt lgkmcnt(1)
	v_mfma_f32_32x32x16_bf16 v[96:111], v[214:217], v[132:135], v[96:111]
	v_add_f32_e32 v213, v220, v213
	s_add_i32 s17, s17, 1
	s_cmp_eq_u32 s17, 4
	v_mfma_f32_32x32x16_bf16 v[112:127], v[136:139], v[128:131], v[112:127]
	s_waitcnt lgkmcnt(0)
	v_mfma_f32_32x32x16_bf16 v[96:111], v[140:143], v[128:131], v[96:111]
	ds_read_b128 v[136:139], v180 offset:40960
	ds_read_b128 v[140:143], v180 offset:45056
	s_waitcnt lgkmcnt(1)
	v_mfma_f32_32x32x16_bf16 v[80:95], v[136:139], v[132:135], v[80:95]
	ds_read_b128 v[136:139], v181 offset:40960
	ds_read_b128 v[214:217], v181 offset:45056
	s_waitcnt lgkmcnt(1)
	v_mfma_f32_32x32x16_bf16 v[80:95], v[136:139], v[128:131], v[80:95]
	v_mfma_f32_32x32x16_bf16 v[64:79], v[140:143], v[132:135], v[64:79]
	ds_read_b128 v[136:139], v180 offset:49152
	ds_read_b128 v[140:143], v180 offset:53248
	s_waitcnt lgkmcnt(1)
	v_mfma_f32_32x32x16_bf16 v[48:63], v[136:139], v[132:135], v[48:63]
	v_mfma_f32_32x32x16_bf16 v[64:79], v[214:217], v[128:131], v[64:79]
	ds_read_b128 v[136:139], v181 offset:49152
	ds_read_b128 v[214:217], v181 offset:53248
	s_waitcnt lgkmcnt(1)
	v_mfma_f32_32x32x16_bf16 v[48:63], v[136:139], v[128:131], v[48:63]
	v_mfma_f32_32x32x16_bf16 v[32:47], v[140:143], v[132:135], v[32:47]
	ds_read_b128 v[136:139], v180 offset:57344
	ds_read_b128 v[140:143], v180 offset:61440
	s_waitcnt lgkmcnt(1)
	v_mfma_f32_32x32x16_bf16 v[16:31], v[136:139], v[132:135], v[16:31]
	v_mfma_f32_32x32x16_bf16 v[32:47], v[214:217], v[128:131], v[32:47]
	ds_read_b128 v[136:139], v181 offset:57344
	ds_read_b128 v[214:217], v181 offset:61440
	s_waitcnt lgkmcnt(2)
	v_mfma_f32_32x32x16_bf16 v[0:15], v[140:143], v[132:135], v[0:15]
	s_waitcnt lgkmcnt(1)
	v_mfma_f32_32x32x16_bf16 v[16:31], v[136:139], v[128:131], v[16:31]
	v_add_f32_e32 v136, v221, v213
	v_add_f32_e32 v136, v222, v136
	v_add_f32_e32 v136, v223, v136
	v_add_f32_e32 v136, v224, v136
	v_add_f32_e32 v136, v225, v136
	v_add_f32_e32 v136, v226, v136
	v_add_f32_e32 v136, v227, v136
	s_waitcnt lgkmcnt(0)
	v_mfma_f32_32x32x16_bf16 v[0:15], v[214:217], v[128:131], v[0:15]
	v_add_f32_e32 v132, v228, v136
	v_add_f32_e32 v132, v229, v132
	v_add_f32_e32 v132, v230, v132
	v_add_f32_e32 v132, v231, v132
	v_add_f32_e32 v132, v232, v132
	v_add_f32_e32 v213, v233, v132
	s_cbranch_scc0 .LBB0_835
	v_mov_b32_e32 v128, v213
	s_nop 1
	v_permlane32_swap_b32_e32 v213, v128
	v_add_f32_e32 v128, v213, v128
	s_andn2_b64 vcc, exec, s[4:5]
	s_barrier
	s_cbranch_vccnz .LBB0_842
	ds_write2st64_b32 v171, v112, v113 offset1:1
	ds_write2st64_b32 v171, v114, v115 offset0:2 offset1:3
	ds_write2st64_b32 v171, v116, v117 offset0:4 offset1:5
	ds_write2st64_b32 v171, v118, v119 offset0:6 offset1:7
	ds_write2st64_b32 v171, v120, v121 offset0:8 offset1:9
	ds_write2st64_b32 v171, v122, v123 offset0:10 offset1:11
	ds_write2st64_b32 v171, v124, v125 offset0:12 offset1:13
	ds_write2st64_b32 v171, v126, v127 offset0:14 offset1:15
	ds_write2st64_b32 v171, v96, v97 offset0:16 offset1:17
	ds_write2st64_b32 v171, v98, v99 offset0:18 offset1:19
	ds_write2st64_b32 v171, v100, v101 offset0:20 offset1:21
	ds_write2st64_b32 v171, v102, v103 offset0:22 offset1:23
	ds_write2st64_b32 v171, v104, v105 offset0:24 offset1:25
	ds_write2st64_b32 v171, v106, v107 offset0:26 offset1:27
	ds_write2st64_b32 v171, v108, v109 offset0:28 offset1:29
	ds_write2st64_b32 v171, v110, v111 offset0:30 offset1:31
	ds_write2st64_b32 v171, v80, v81 offset0:32 offset1:33
	ds_write2st64_b32 v171, v82, v83 offset0:34 offset1:35
	ds_write2st64_b32 v171, v84, v85 offset0:36 offset1:37
	ds_write2st64_b32 v171, v86, v87 offset0:38 offset1:39
	ds_write2st64_b32 v171, v88, v89 offset0:40 offset1:41
	ds_write2st64_b32 v171, v90, v91 offset0:42 offset1:43
	ds_write2st64_b32 v171, v92, v93 offset0:44 offset1:45
	ds_write2st64_b32 v171, v94, v95 offset0:46 offset1:47
	ds_write2st64_b32 v171, v64, v65 offset0:48 offset1:49
	ds_write2st64_b32 v171, v66, v67 offset0:50 offset1:51
	ds_write2st64_b32 v171, v68, v69 offset0:52 offset1:53
	ds_write2st64_b32 v171, v70, v71 offset0:54 offset1:55
	ds_write2st64_b32 v171, v72, v73 offset0:56 offset1:57
	ds_write2st64_b32 v171, v74, v75 offset0:58 offset1:59
	ds_write2st64_b32 v171, v76, v77 offset0:60 offset1:61
	ds_write2st64_b32 v171, v78, v79 offset0:62 offset1:63
	ds_write2st64_b32 v171, v48, v49 offset0:64 offset1:65
	ds_write2st64_b32 v171, v50, v51 offset0:66 offset1:67
	ds_write2st64_b32 v171, v52, v53 offset0:68 offset1:69
	ds_write2st64_b32 v171, v54, v55 offset0:70 offset1:71
	ds_write2st64_b32 v171, v56, v57 offset0:72 offset1:73
	ds_write2st64_b32 v171, v58, v59 offset0:74 offset1:75
	ds_write2st64_b32 v171, v60, v61 offset0:76 offset1:77
	ds_write2st64_b32 v171, v62, v63 offset0:78 offset1:79
	ds_write2st64_b32 v171, v32, v33 offset0:80 offset1:81
	ds_write2st64_b32 v171, v34, v35 offset0:82 offset1:83
	ds_write2st64_b32 v171, v36, v37 offset0:84 offset1:85
	ds_write2st64_b32 v171, v38, v39 offset0:86 offset1:87
	ds_write2st64_b32 v171, v40, v41 offset0:88 offset1:89
	ds_write2st64_b32 v171, v42, v43 offset0:90 offset1:91
	ds_write2st64_b32 v171, v44, v45 offset0:92 offset1:93
	ds_write2st64_b32 v171, v46, v47 offset0:94 offset1:95
	ds_write2st64_b32 v171, v16, v17 offset0:96 offset1:97
	ds_write2st64_b32 v171, v18, v19 offset0:98 offset1:99
	ds_write2st64_b32 v171, v20, v21 offset0:100 offset1:101
	ds_write2st64_b32 v171, v22, v23 offset0:102 offset1:103
	ds_write2st64_b32 v171, v24, v25 offset0:104 offset1:105
	ds_write2st64_b32 v171, v26, v27 offset0:106 offset1:107
	ds_write2st64_b32 v171, v28, v29 offset0:108 offset1:109
	ds_write2st64_b32 v171, v30, v31 offset0:110 offset1:111
	ds_write2st64_b32 v171, v0, v1 offset0:112 offset1:113
	ds_write2st64_b32 v171, v2, v3 offset0:114 offset1:115
	ds_write2st64_b32 v171, v4, v5 offset0:116 offset1:117
	ds_write2st64_b32 v171, v6, v7 offset0:118 offset1:119
	ds_write2st64_b32 v171, v8, v9 offset0:120 offset1:121
	ds_write2st64_b32 v171, v10, v11 offset0:122 offset1:123
	ds_write2st64_b32 v171, v12, v13 offset0:124 offset1:125
	ds_write2st64_b32 v171, v14, v15 offset0:126 offset1:127
	v_add_u32_e32 v129, s12, v161
	ds_write_b32 v129, v128
